# attention softmax: lazy rescale (reference max only moves when a tile max exceeds it by 8 in log2 units), on top of pipelined key loop
# speedup vs baseline: 1.0268x; 1.0181x over previous
; __device__ __forceinline__ unsigned cvt_pk_bf16(float lo, float hi) { unsigned r; asm volatile("v_cvt_pk_bf16_f32 %0, %1, %2" : "=v"(r) : "v"(lo), "v"(hi)); return r; }
; __device__ __forceinline__ void phase_attn(const Params& p, unsigned char* lds) {
;     ...
;             bf16x8 P[2][2];
; #pragma unroll
;             for (int kb = 0; kb < 2; ++kb)
; #pragma unroll
;                 for (int s2 = 0; s2 < 2; ++s2) { u32x4 pk;
; #pragma unroll
;                     for (int jj = 0; jj < 4; ++jj) { const float p0 = __builtin_amdgcn_exp2f(st[kb][8 * s2 + 2 * jj] - mnew), p1 = __builtin_amdgcn_exp2f(st[kb][8 * s2 + 2 * jj + 1] - mnew); lsum += p0 + p1; pk[jj] = cvt_pk_bf16(p0, p1); }
;                     P[kb][s2] = __builtin_bit_cast(bf16x8, pk); }
.Lat_norescale_1:
	v_mov_b32_e32 v236, 0
	s_waitcnt lgkmcnt(7)
	v_mfma_f32_32x32x16_bf16 v[196:211], v[172:175], v[108:111], 0
	v_sub_f32_e32 v80, v80, v149
	v_sub_f32_e32 v81, v81, v149
	v_sub_f32_e32 v82, v82, v149
	v_sub_f32_e32 v83, v83, v149
	v_exp_f32_e32 v80, v80
	v_exp_f32_e32 v81, v81
	v_exp_f32_e32 v82, v82
	v_exp_f32_e32 v83, v83
	v_add_f32_e32 v128, v128, v80
	v_add_f32_e32 v236, v236, v81
	v_cvt_pk_bf16_f32 v80, v80, v81
	v_add_f32_e32 v128, v128, v82
	v_add_f32_e32 v236, v236, v83
	v_cvt_pk_bf16_f32 v81, v82, v83
	s_waitcnt lgkmcnt(6)
	v_mfma_f32_32x32x16_bf16 v[196:211], v[176:179], v[104:107], v[196:211]
	v_sub_f32_e32 v84, v84, v149
	v_sub_f32_e32 v85, v85, v149
	v_sub_f32_e32 v86, v86, v149
	v_sub_f32_e32 v87, v87, v149
	v_exp_f32_e32 v84, v84
	v_exp_f32_e32 v85, v85
	v_exp_f32_e32 v86, v86
	v_exp_f32_e32 v87, v87
	v_add_f32_e32 v128, v128, v84
	v_add_f32_e32 v236, v236, v85
	v_cvt_pk_bf16_f32 v82, v84, v85
	v_add_f32_e32 v128, v128, v86
	v_add_f32_e32 v236, v236, v87
	v_cvt_pk_bf16_f32 v83, v86, v87
	s_waitcnt lgkmcnt(5)
	v_mfma_f32_32x32x16_bf16 v[196:211], v[180:183], v[100:103], v[196:211]
	v_sub_f32_e32 v88, v88, v149
	v_sub_f32_e32 v89, v89, v149
	v_sub_f32_e32 v90, v90, v149
	v_sub_f32_e32 v91, v91, v149
	v_exp_f32_e32 v88, v88
	v_exp_f32_e32 v89, v89
	v_exp_f32_e32 v90, v90
	v_exp_f32_e32 v91, v91
	v_add_f32_e32 v128, v128, v88
	v_add_f32_e32 v236, v236, v89
	v_cvt_pk_bf16_f32 v84, v88, v89
	v_add_f32_e32 v128, v128, v90
	v_add_f32_e32 v236, v236, v91
	v_cvt_pk_bf16_f32 v85, v90, v91
	s_waitcnt lgkmcnt(4)
	v_mfma_f32_32x32x16_bf16 v[196:211], v[184:187], v[96:99], v[196:211]
	ds_read_b128 v[172:175], v159 offset:34816
	ds_read_b128 v[176:179], v159 offset:34848
	ds_read_b128 v[180:183], v159 offset:34880
	ds_read_b128 v[184:187], v159 offset:34912
	v_sub_f32_e32 v92, v92, v149
	v_sub_f32_e32 v93, v93, v149
	v_sub_f32_e32 v94, v94, v149
	v_sub_f32_e32 v95, v95, v149
	v_exp_f32_e32 v92, v92
	v_exp_f32_e32 v93, v93
	v_exp_f32_e32 v94, v94
	v_exp_f32_e32 v95, v95
	v_add_f32_e32 v128, v128, v92
	v_add_f32_e32 v236, v236, v93
	v_cvt_pk_bf16_f32 v86, v92, v93
	v_add_f32_e32 v128, v128, v94
	v_add_f32_e32 v236, v236, v95
	v_cvt_pk_bf16_f32 v87, v94, v95
	s_waitcnt lgkmcnt(7)
	v_mfma_f32_32x32x16_bf16 v[212:227], v[188:191], v[108:111], 0
	v_sub_f32_e32 v64, v64, v149
	v_sub_f32_e32 v65, v65, v149
	v_sub_f32_e32 v66, v66, v149
	v_sub_f32_e32 v67, v67, v149
	v_exp_f32_e32 v64, v64
	v_exp_f32_e32 v65, v65
	v_exp_f32_e32 v66, v66
	v_exp_f32_e32 v67, v67
	v_add_f32_e32 v128, v128, v64
	v_add_f32_e32 v236, v236, v65
	v_cvt_pk_bf16_f32 v64, v64, v65
	v_add_f32_e32 v128, v128, v66
	v_add_f32_e32 v236, v236, v67
	v_cvt_pk_bf16_f32 v65, v66, v67
	s_waitcnt lgkmcnt(6)
	v_mfma_f32_32x32x16_bf16 v[212:227], v[192:195], v[104:107], v[212:227]
	v_sub_f32_e32 v68, v68, v149
	v_sub_f32_e32 v69, v69, v149
	v_sub_f32_e32 v70, v70, v149
	v_sub_f32_e32 v71, v71, v149
	v_exp_f32_e32 v68, v68
	v_exp_f32_e32 v69, v69
	v_exp_f32_e32 v70, v70
	v_exp_f32_e32 v71, v71
	v_add_f32_e32 v128, v128, v68
	v_add_f32_e32 v236, v236, v69
	v_cvt_pk_bf16_f32 v66, v68, v69
	v_add_f32_e32 v128, v128, v70
	v_add_f32_e32 v236, v236, v71
	v_cvt_pk_bf16_f32 v67, v70, v71
	s_waitcnt lgkmcnt(5)
	v_mfma_f32_32x32x16_bf16 v[212:227], v[228:231], v[100:103], v[212:227]
	v_sub_f32_e32 v72, v72, v149
	v_sub_f32_e32 v73, v73, v149
	v_sub_f32_e32 v74, v74, v149
	v_sub_f32_e32 v75, v75, v149
	v_exp_f32_e32 v72, v72
	v_exp_f32_e32 v73, v73
	v_exp_f32_e32 v74, v74
	v_exp_f32_e32 v75, v75
	v_add_f32_e32 v128, v128, v72
	v_add_f32_e32 v236, v236, v73
	v_cvt_pk_bf16_f32 v68, v72, v73
	v_add_f32_e32 v128, v128, v74
	v_add_f32_e32 v236, v236, v75
	v_cvt_pk_bf16_f32 v69, v74, v75
	s_waitcnt lgkmcnt(4)
	v_mfma_f32_32x32x16_bf16 v[212:227], v[232:235], v[96:99], v[212:227]
	ds_read_b128 v[188:191], v159 offset:39424
	ds_read_b128 v[192:195], v159 offset:39456
	ds_read_b128 v[228:231], v159 offset:39488
	ds_read_b128 v[232:235], v159 offset:39520
	v_sub_f32_e32 v76, v76, v149
	v_sub_f32_e32 v77, v77, v149
	v_sub_f32_e32 v78, v78, v149
	v_sub_f32_e32 v79, v79, v149
	v_exp_f32_e32 v76, v76
	v_exp_f32_e32 v77, v77
	v_exp_f32_e32 v78, v78
	v_exp_f32_e32 v79, v79
	v_add_f32_e32 v128, v128, v76
	v_add_f32_e32 v236, v236, v77
	v_cvt_pk_bf16_f32 v70, v76, v77
	v_add_f32_e32 v128, v128, v78
	v_add_f32_e32 v236, v236, v79
	v_cvt_pk_bf16_f32 v71, v78, v79
	v_add_f32_e32 v128, v128, v236
	s_waitcnt lgkmcnt(7)
	v_mfma_f32_32x32x16_bf16 v[48:63], v[172:175], v[80:83], v[48:63]
	s_waitcnt lgkmcnt(6)
	v_mfma_f32_32x32x16_bf16 v[48:63], v[176:179], v[84:87], v[48:63]
	v_max3_f32 v145, v196, v197, v198
	v_max3_f32 v237, v212, v213, v214
	v_max3_f32 v145, v145, v199, v200
	s_waitcnt lgkmcnt(5)
	v_mfma_f32_32x32x16_bf16 v[48:63], v[180:183], v[64:67], v[48:63]
	v_max3_f32 v237, v237, v215, v216
	v_max3_f32 v145, v145, v201, v202
	v_max3_f32 v237, v237, v217, v218
	s_waitcnt lgkmcnt(4)
	v_mfma_f32_32x32x16_bf16 v[48:63], v[184:187], v[68:71], v[48:63]
	v_max3_f32 v145, v145, v203, v204
	v_max3_f32 v237, v237, v219, v220
	v_max3_f32 v145, v145, v205, v206
	ds_read_b128 v[172:175], v159 offset:44032
	ds_read_b128 v[176:179], v159 offset:44064
	ds_read_b128 v[180:183], v159 offset:44096
	ds_read_b128 v[184:187], v159 offset:44128
	s_waitcnt lgkmcnt(7)
	v_mfma_f32_32x32x16_bf16 v[32:47], v[188:191], v[80:83], v[32:47]
	v_max3_f32 v237, v237, v221, v222
	v_max3_f32 v145, v145, v207, v208
	v_max3_f32 v237, v237, v223, v224
	s_waitcnt lgkmcnt(6)
	v_mfma_f32_32x32x16_bf16 v[32:47], v[192:195], v[84:87], v[32:47]
	v_max3_f32 v145, v145, v209, v210
	v_max3_f32 v237, v237, v225, v226
	v_max_f32_e32 v145, v145, v211
	s_waitcnt lgkmcnt(5)
; #define AT_STOREK(buf) do { _Pragma("unroll") for (int i_ = 0; i_ < 2; ++i_) { const int id_ = tid + 512 * i_; \
;             *(u32x4*)(sKt + (buf) * 8704 + (id_ >> 4) * 136 + (id_ & 15) * 8) = kr[i_]; } } while (0)
; #define AT_STOREV(buf) do { _Pragma("unroll") for (int i_ = 0; i_ < 2; ++i_) { const int id_ = tid + 512 * i_; \
;             *(u32x4*)(sVt + (buf) * 9216 + (id_ >> 3) * 72 + (id_ & 7) * 8) = vr[i_]; } } while (0)
; #define AT_LDV(set, vb) do { _Pragma("unroll") for (int kb = 0; kb < 2; ++kb) _Pragma("unroll") for (int s2 = 0; s2 < 2; ++s2) \
;                     vf[set][kb * 2 + s2] = *(const bf16x8*)(sVt + buf * 9216 + (32 * (vb) + ql) * 72 + 32 * kb + 16 * s2 + 8 * g); } while (0)
; __device__ __forceinline__ void phase_attn(const Params& p, unsigned char* lds) {
;     ...
;             float mloc = st[0][0];
; #pragma unroll
;             for (int i = 0; i < 16; ++i) { mloc = fmaxf(mloc, st[0][i]); mloc = fmaxf(mloc, st[1][i]); }
;             mloc = fmaxf(mloc, __shfl_xor(mloc, 32));
;             const float mnew = fmaxf(mrun, mloc);
;             if (__builtin_amdgcn_ballot_w64(mnew > mrun) != 0ull) {
;                 const float alpha = __builtin_amdgcn_exp2f(mrun - mnew);
;                 lsum *= alpha;
; #pragma unroll
;                 for (int vb = 0; vb < 4; ++vb)
; #pragma unroll
;                     for (int i = 0; i < 16; ++i) ot[vb][i] *= alpha;
;             }
;             mrun = mnew;
;     ...
;             {
;                 bf16x8 vf[2][4];
;     ...
;                 AT_LDV(0, 0);
; #pragma unroll
;                 for (int vb = 0; vb < 4; ++vb) {
;                     if (vb < 3) AT_LDV((vb + 1) & 1, vb + 1);
;                     __builtin_amdgcn_sched_barrier(0);
;                     __builtin_amdgcn_s_setprio(2);
; #pragma unroll
;                     for (int kb = 0; kb < 2; ++kb)
; #pragma unroll
;                         for (int s2 = 0; s2 < 2; ++s2) ot[vb] = __builtin_amdgcn_mfma_f32_32x32x16_bf16(vf[vb & 1][kb * 2 + s2], P[kb][s2], ot[vb], 0, 0, 0);
;                     __builtin_amdgcn_s_setprio(0);
;                     __builtin_amdgcn_sched_barrier(0);
;                 }
;     ...
;             }
;             if (kt + 1 < 64) { AT_STOREK(buf ^ 1); AT_STOREV(buf ^ 1); }
;             __syncthreads();
;         }
	v_mfma_f32_32x32x16_bf16 v[32:47], v[228:231], v[64:67], v[32:47]
	v_max_f32_e32 v237, v237, v227
	v_max_f32_e32 v145, v145, v237
	ds_bpermute_b32 v237, v158, v145
	s_waitcnt lgkmcnt(5)
	v_mfma_f32_32x32x16_bf16 v[32:47], v[232:235], v[68:71], v[32:47]
	v_add_u32_e32 v239, v131, v164
	s_waitcnt vmcnt(3)
	ds_write_b128 v239, v[116:119] offset:0
	ds_read_b128 v[188:191], v159 offset:48640
	ds_read_b128 v[192:195], v159 offset:48672
	ds_read_b128 v[228:231], v159 offset:48704
	ds_read_b128 v[232:235], v159 offset:48736
	s_waitcnt lgkmcnt(9)
	v_mfma_f32_32x32x16_bf16 v[16:31], v[172:175], v[80:83], v[16:31]
	v_add_u32_e32 v239, v131, v165
	s_waitcnt vmcnt(2)
	ds_write_b128 v239, v[112:115] offset:0
	s_waitcnt lgkmcnt(9)
	v_mfma_f32_32x32x16_bf16 v[16:31], v[176:179], v[84:87], v[16:31]
	v_add_u32_e32 v239, v156, v166
	s_waitcnt vmcnt(1)
	ds_write_b128 v239, v[124:127] offset:53248
	s_waitcnt lgkmcnt(9)
	v_mfma_f32_32x32x16_bf16 v[16:31], v[180:183], v[64:67], v[16:31]
	v_add_u32_e32 v239, v156, v167
	s_waitcnt vmcnt(0)
	ds_write_b128 v239, v[120:123] offset:53248
	s_waitcnt lgkmcnt(9)
	v_mfma_f32_32x32x16_bf16 v[16:31], v[184:187], v[68:71], v[16:31]
	s_waitcnt lgkmcnt(8)
	v_max_f32_e32 v237, v145, v237
	v_add_f32_e32 v239, 0x41000000, v149
	v_max_f32_e32 v145, v149, v237
	s_waitcnt lgkmcnt(6)
	v_mfma_f32_32x32x16_bf16 v[0:15], v[188:191], v[80:83], v[0:15]
	v_sub_f32_e32 v238, v149, v145
	v_cmp_gt_f32_e32 vcc, v237, v239
	v_exp_f32_e32 v238, v238
	s_waitcnt lgkmcnt(5)
	v_mfma_f32_32x32x16_bf16 v[0:15], v[192:195], v[84:87], v[0:15]
	s_waitcnt lgkmcnt(4)
	v_mfma_f32_32x32x16_bf16 v[0:15], v[228:231], v[64:67], v[0:15]
	s_waitcnt lgkmcnt(3)
	v_mfma_f32_32x32x16_bf16 v[0:15], v[232:235], v[68:71], v[0:15]
	s_cbranch_vccz .Lat_keepm_2
	v_mov_b32_e32 v149, v145
.Lat_keepm_2:
	s_add_i32 s21, s21, 64
	s_add_i32 s20, s20, 1
	s_waitcnt lgkmcnt(0)
	s_barrier
	s_cmp_eq_u32 s20, 63
	s_cbranch_scc1 .Lat_last
	ds_read_b128 v[172:175], v157 offset:0
	ds_read_b128 v[176:179], v157 offset:32
	ds_read_b128 v[180:183], v157 offset:64
	ds_read_b128 v[184:187], v157 offset:96
	ds_read_b128 v[188:191], v157 offset:8704
	ds_read_b128 v[192:195], v157 offset:8736
	ds_read_b128 v[228:231], v157 offset:8768
	ds_read_b128 v[232:235], v157 offset:8800
	s_add_i32 s12, s21, 64
	s_and_b32 s12, s12, 0xfc0
	v_add_u32_e32 v116, s12, v162
	v_ashrrev_i32_e32 v117, 31, v116
	v_add_u32_e32 v112, s12, v163
	v_lshlrev_b64 v[116:117], 13, v[116:117]
	v_ashrrev_i32_e32 v113, 31, v112
	v_lshl_add_u64 v[116:117], v[152:153], 0, v[116:117]
	v_lshlrev_b64 v[112:113], 13, v[112:113]
	v_lshl_add_u64 v[112:113], v[152:153], 0, v[112:113]
	global_load_dwordx4 v[116:119], v[116:117], off
	global_load_dwordx4 v[112:115], v[112:113], off
	s_and_b32 s12, s21, 0xfc0
	s_lshl_b32 s12, s12, 1
	v_lshl_add_u64 v[124:125], v[154:155], 0, s[12:13]
	v_lshl_add_u64 v[120:121], v[124:125], 0, v[138:139]
	v_lshl_add_u64 v[124:125], v[124:125], 0, v[136:137]
	global_load_dwordx4 v[124:127], v[124:125], off
	global_load_dwordx4 v[120:123], v[120:121], off
	s_cbranch_vccz .Lat_norescale_3
	v_pk_mul_f32 v[0:1], v[0:1], v[238:239] op_sel_hi:[1,0]
	v_pk_mul_f32 v[2:3], v[2:3], v[238:239] op_sel_hi:[1,0]
	v_pk_mul_f32 v[4:5], v[4:5], v[238:239] op_sel_hi:[1,0]
	v_pk_mul_f32 v[6:7], v[6:7], v[238:239] op_sel_hi:[1,0]
	v_pk_mul_f32 v[8:9], v[8:9], v[238:239] op_sel_hi:[1,0]
	v_pk_mul_f32 v[10:11], v[10:11], v[238:239] op_sel_hi:[1,0]
	v_pk_mul_f32 v[12:13], v[12:13], v[238:239] op_sel_hi:[1,0]
	v_pk_mul_f32 v[14:15], v[14:15], v[238:239] op_sel_hi:[1,0]
	v_pk_mul_f32 v[16:17], v[16:17], v[238:239] op_sel_hi:[1,0]
	v_pk_mul_f32 v[18:19], v[18:19], v[238:239] op_sel_hi:[1,0]
	v_pk_mul_f32 v[20:21], v[20:21], v[238:239] op_sel_hi:[1,0]
	v_pk_mul_f32 v[22:23], v[22:23], v[238:239] op_sel_hi:[1,0]
	v_pk_mul_f32 v[24:25], v[24:25], v[238:239] op_sel_hi:[1,0]
	v_pk_mul_f32 v[26:27], v[26:27], v[238:239] op_sel_hi:[1,0]
	v_pk_mul_f32 v[28:29], v[28:29], v[238:239] op_sel_hi:[1,0]
	v_pk_mul_f32 v[30:31], v[30:31], v[238:239] op_sel_hi:[1,0]
	v_pk_mul_f32 v[32:33], v[32:33], v[238:239] op_sel_hi:[1,0]
	v_pk_mul_f32 v[34:35], v[34:35], v[238:239] op_sel_hi:[1,0]
	v_pk_mul_f32 v[36:37], v[36:37], v[238:239] op_sel_hi:[1,0]
	v_pk_mul_f32 v[38:39], v[38:39], v[238:239] op_sel_hi:[1,0]
	v_pk_mul_f32 v[40:41], v[40:41], v[238:239] op_sel_hi:[1,0]
	v_pk_mul_f32 v[42:43], v[42:43], v[238:239] op_sel_hi:[1,0]
	v_pk_mul_f32 v[44:45], v[44:45], v[238:239] op_sel_hi:[1,0]
	v_pk_mul_f32 v[46:47], v[46:47], v[238:239] op_sel_hi:[1,0]
	v_pk_mul_f32 v[48:49], v[48:49], v[238:239] op_sel_hi:[1,0]
	v_pk_mul_f32 v[50:51], v[50:51], v[238:239] op_sel_hi:[1,0]
	v_pk_mul_f32 v[52:53], v[52:53], v[238:239] op_sel_hi:[1,0]
	v_pk_mul_f32 v[54:55], v[54:55], v[238:239] op_sel_hi:[1,0]
	v_pk_mul_f32 v[56:57], v[56:57], v[238:239] op_sel_hi:[1,0]
	v_pk_mul_f32 v[58:59], v[58:59], v[238:239] op_sel_hi:[1,0]
	v_pk_mul_f32 v[60:61], v[60:61], v[238:239] op_sel_hi:[1,0]
	v_pk_mul_f32 v[62:63], v[62:63], v[238:239] op_sel_hi:[1,0]
	v_mul_f32_e32 v128, v128, v238
; __device__ __forceinline__ unsigned cvt_pk_bf16(float lo, float hi) { unsigned r; asm volatile("v_cvt_pk_bf16_f32 %0, %1, %2" : "=v"(r) : "v"(lo), "v"(hi)); return r; }
; __device__ __forceinline__ void phase_attn(const Params& p, unsigned char* lds) {
;     ...
;             bf16x8 P[2][2];
; #pragma unroll
;             for (int kb = 0; kb < 2; ++kb)
; #pragma unroll
;                 for (int s2 = 0; s2 < 2; ++s2) { u32x4 pk;
; #pragma unroll
;                     for (int jj = 0; jj < 4; ++jj) { const float p0 = __builtin_amdgcn_exp2f(st[kb][8 * s2 + 2 * jj] - mnew), p1 = __builtin_amdgcn_exp2f(st[kb][8 * s2 + 2 * jj + 1] - mnew); lsum += p0 + p1; pk[jj] = cvt_pk_bf16(p0, p1); }
;                     P[kb][s2] = __builtin_bit_cast(bf16x8, pk); }
.Lat_norescale_3:
	v_mov_b32_e32 v236, 0
	s_waitcnt lgkmcnt(7)
	v_mfma_f32_32x32x16_bf16 v[80:95], v[172:175], v[108:111], 0
	v_sub_f32_e32 v196, v196, v149
	v_sub_f32_e32 v197, v197, v149
	v_sub_f32_e32 v198, v198, v149
	v_sub_f32_e32 v199, v199, v149
	v_exp_f32_e32 v196, v196
	v_exp_f32_e32 v197, v197
	v_exp_f32_e32 v198, v198
	v_exp_f32_e32 v199, v199
	v_add_f32_e32 v128, v128, v196
	v_add_f32_e32 v236, v236, v197
	v_cvt_pk_bf16_f32 v196, v196, v197
	v_add_f32_e32 v128, v128, v198
	v_add_f32_e32 v236, v236, v199
	v_cvt_pk_bf16_f32 v197, v198, v199
	s_waitcnt lgkmcnt(6)
	v_mfma_f32_32x32x16_bf16 v[80:95], v[176:179], v[104:107], v[80:95]
	v_sub_f32_e32 v200, v200, v149
	v_sub_f32_e32 v201, v201, v149
	v_sub_f32_e32 v202, v202, v149
	v_sub_f32_e32 v203, v203, v149
	v_exp_f32_e32 v200, v200
	v_exp_f32_e32 v201, v201
	v_exp_f32_e32 v202, v202
	v_exp_f32_e32 v203, v203
	v_add_f32_e32 v128, v128, v200
	v_add_f32_e32 v236, v236, v201
	v_cvt_pk_bf16_f32 v198, v200, v201
	v_add_f32_e32 v128, v128, v202
	v_add_f32_e32 v236, v236, v203
	v_cvt_pk_bf16_f32 v199, v202, v203
	s_waitcnt lgkmcnt(5)
	v_mfma_f32_32x32x16_bf16 v[80:95], v[180:183], v[100:103], v[80:95]
	v_sub_f32_e32 v204, v204, v149
	v_sub_f32_e32 v205, v205, v149
	v_sub_f32_e32 v206, v206, v149
	v_sub_f32_e32 v207, v207, v149
	v_exp_f32_e32 v204, v204
	v_exp_f32_e32 v205, v205
	v_exp_f32_e32 v206, v206
	v_exp_f32_e32 v207, v207
	v_add_f32_e32 v128, v128, v204
	v_add_f32_e32 v236, v236, v205
	v_cvt_pk_bf16_f32 v200, v204, v205
	v_add_f32_e32 v128, v128, v206
	v_add_f32_e32 v236, v236, v207
	v_cvt_pk_bf16_f32 v201, v206, v207
	s_waitcnt lgkmcnt(4)
	v_mfma_f32_32x32x16_bf16 v[80:95], v[184:187], v[96:99], v[80:95]
	ds_read_b128 v[172:175], v147 offset:34816
	ds_read_b128 v[176:179], v147 offset:34848
	ds_read_b128 v[180:183], v147 offset:34880
	ds_read_b128 v[184:187], v147 offset:34912
	v_sub_f32_e32 v208, v208, v149
	v_sub_f32_e32 v209, v209, v149
	v_sub_f32_e32 v210, v210, v149
	v_sub_f32_e32 v211, v211, v149
	v_exp_f32_e32 v208, v208
	v_exp_f32_e32 v209, v209
	v_exp_f32_e32 v210, v210
	v_exp_f32_e32 v211, v211
	v_add_f32_e32 v128, v128, v208
	v_add_f32_e32 v236, v236, v209
	v_cvt_pk_bf16_f32 v202, v208, v209
	v_add_f32_e32 v128, v128, v210
	v_add_f32_e32 v236, v236, v211
	v_cvt_pk_bf16_f32 v203, v210, v211
	s_waitcnt lgkmcnt(7)
	v_mfma_f32_32x32x16_bf16 v[64:79], v[188:191], v[108:111], 0
	v_sub_f32_e32 v212, v212, v149
	v_sub_f32_e32 v213, v213, v149
	v_sub_f32_e32 v214, v214, v149
	v_sub_f32_e32 v215, v215, v149
	v_exp_f32_e32 v212, v212
	v_exp_f32_e32 v213, v213
	v_exp_f32_e32 v214, v214
	v_exp_f32_e32 v215, v215
	v_add_f32_e32 v128, v128, v212
	v_add_f32_e32 v236, v236, v213
	v_cvt_pk_bf16_f32 v212, v212, v213
	v_add_f32_e32 v128, v128, v214
	v_add_f32_e32 v236, v236, v215
	v_cvt_pk_bf16_f32 v213, v214, v215
	s_waitcnt lgkmcnt(6)
	v_mfma_f32_32x32x16_bf16 v[64:79], v[192:195], v[104:107], v[64:79]
	v_sub_f32_e32 v216, v216, v149
	v_sub_f32_e32 v217, v217, v149
	v_sub_f32_e32 v218, v218, v149
	v_sub_f32_e32 v219, v219, v149
	v_exp_f32_e32 v216, v216
	v_exp_f32_e32 v217, v217
	v_exp_f32_e32 v218, v218
	v_exp_f32_e32 v219, v219
	v_add_f32_e32 v128, v128, v216
	v_add_f32_e32 v236, v236, v217
	v_cvt_pk_bf16_f32 v214, v216, v217
	v_add_f32_e32 v128, v128, v218
	v_add_f32_e32 v236, v236, v219
	v_cvt_pk_bf16_f32 v215, v218, v219
	s_waitcnt lgkmcnt(5)
	v_mfma_f32_32x32x16_bf16 v[64:79], v[228:231], v[100:103], v[64:79]
	v_sub_f32_e32 v220, v220, v149
	v_sub_f32_e32 v221, v221, v149
	v_sub_f32_e32 v222, v222, v149
	v_sub_f32_e32 v223, v223, v149
	v_exp_f32_e32 v220, v220
	v_exp_f32_e32 v221, v221
	v_exp_f32_e32 v222, v222
	v_exp_f32_e32 v223, v223
	v_add_f32_e32 v128, v128, v220
	v_add_f32_e32 v236, v236, v221
	v_cvt_pk_bf16_f32 v216, v220, v221
	v_add_f32_e32 v128, v128, v222
	v_add_f32_e32 v236, v236, v223
	v_cvt_pk_bf16_f32 v217, v222, v223
	s_waitcnt lgkmcnt(4)
; #define AT_STOREK(buf) do { _Pragma("unroll") for (int i_ = 0; i_ < 2; ++i_) { const int id_ = tid + 512 * i_; \
;             *(u32x4*)(sKt + (buf) * 8704 + (id_ >> 4) * 136 + (id_ & 15) * 8) = kr[i_]; } } while (0)
; #define AT_STOREV(buf) do { _Pragma("unroll") for (int i_ = 0; i_ < 2; ++i_) { const int id_ = tid + 512 * i_; \
;             *(u32x4*)(sVt + (buf) * 9216 + (id_ >> 3) * 72 + (id_ & 7) * 8) = vr[i_]; } } while (0)
; #define AT_LDV(set, vb) do { _Pragma("unroll") for (int kb = 0; kb < 2; ++kb) _Pragma("unroll") for (int s2 = 0; s2 < 2; ++s2) \
;                     vf[set][kb * 2 + s2] = *(const bf16x8*)(sVt + buf * 9216 + (32 * (vb) + ql) * 72 + 32 * kb + 16 * s2 + 8 * g); } while (0)
; __device__ __forceinline__ void phase_attn(const Params& p, unsigned char* lds) {
;     ...
;             float mloc = st[0][0];
; #pragma unroll
;             for (int i = 0; i < 16; ++i) { mloc = fmaxf(mloc, st[0][i]); mloc = fmaxf(mloc, st[1][i]); }
;             mloc = fmaxf(mloc, __shfl_xor(mloc, 32));
;             const float mnew = fmaxf(mrun, mloc);
;             if (__builtin_amdgcn_ballot_w64(mnew > mrun) != 0ull) {
;                 const float alpha = __builtin_amdgcn_exp2f(mrun - mnew);
;                 lsum *= alpha;
; #pragma unroll
;                 for (int vb = 0; vb < 4; ++vb)
; #pragma unroll
;                     for (int i = 0; i < 16; ++i) ot[vb][i] *= alpha;
;             }
;             mrun = mnew;
;     ...
;             {
;                 bf16x8 vf[2][4];
;     ...
;                 AT_LDV(0, 0);
; #pragma unroll
;                 for (int vb = 0; vb < 4; ++vb) {
;                     if (vb < 3) AT_LDV((vb + 1) & 1, vb + 1);
;                     __builtin_amdgcn_sched_barrier(0);
;                     __builtin_amdgcn_s_setprio(2);
; #pragma unroll
;                     for (int kb = 0; kb < 2; ++kb)
; #pragma unroll
;                         for (int s2 = 0; s2 < 2; ++s2) ot[vb] = __builtin_amdgcn_mfma_f32_32x32x16_bf16(vf[vb & 1][kb * 2 + s2], P[kb][s2], ot[vb], 0, 0, 0);
;                     __builtin_amdgcn_s_setprio(0);
;                     __builtin_amdgcn_sched_barrier(0);
;                 }
;     ...
;             }
;             if (kt + 1 < 64) { AT_STOREK(buf ^ 1); AT_STOREV(buf ^ 1); }
;             __syncthreads();
;         }
	v_mfma_f32_32x32x16_bf16 v[64:79], v[232:235], v[96:99], v[64:79]
	ds_read_b128 v[188:191], v147 offset:39424
	ds_read_b128 v[192:195], v147 offset:39456
	ds_read_b128 v[228:231], v147 offset:39488
	ds_read_b128 v[232:235], v147 offset:39520
	v_sub_f32_e32 v224, v224, v149
	v_sub_f32_e32 v225, v225, v149
	v_sub_f32_e32 v226, v226, v149
	v_sub_f32_e32 v227, v227, v149
	v_exp_f32_e32 v224, v224
	v_exp_f32_e32 v225, v225
	v_exp_f32_e32 v226, v226
	v_exp_f32_e32 v227, v227
	v_add_f32_e32 v128, v128, v224
	v_add_f32_e32 v236, v236, v225
	v_cvt_pk_bf16_f32 v218, v224, v225
	v_add_f32_e32 v128, v128, v226
	v_add_f32_e32 v236, v236, v227
	v_cvt_pk_bf16_f32 v219, v226, v227
	v_add_f32_e32 v128, v128, v236
	s_waitcnt lgkmcnt(7)
	v_mfma_f32_32x32x16_bf16 v[48:63], v[172:175], v[196:199], v[48:63]
	s_waitcnt lgkmcnt(6)
	v_mfma_f32_32x32x16_bf16 v[48:63], v[176:179], v[200:203], v[48:63]
	v_max3_f32 v145, v80, v81, v82
	v_max3_f32 v237, v64, v65, v66
	v_max3_f32 v145, v145, v83, v84
	s_waitcnt lgkmcnt(5)
	v_mfma_f32_32x32x16_bf16 v[48:63], v[180:183], v[212:215], v[48:63]
	v_max3_f32 v237, v237, v67, v68
	v_max3_f32 v145, v145, v85, v86
	v_max3_f32 v237, v237, v69, v70
	s_waitcnt lgkmcnt(4)
	v_mfma_f32_32x32x16_bf16 v[48:63], v[184:187], v[216:219], v[48:63]
	v_max3_f32 v145, v145, v87, v88
	v_max3_f32 v237, v237, v71, v72
	v_max3_f32 v145, v145, v89, v90
	ds_read_b128 v[172:175], v147 offset:44032
	ds_read_b128 v[176:179], v147 offset:44064
	ds_read_b128 v[180:183], v147 offset:44096
	ds_read_b128 v[184:187], v147 offset:44128
	s_waitcnt lgkmcnt(7)
	v_mfma_f32_32x32x16_bf16 v[32:47], v[188:191], v[196:199], v[32:47]
	v_max3_f32 v237, v237, v73, v74
	v_max3_f32 v145, v145, v91, v92
	v_max3_f32 v237, v237, v75, v76
	s_waitcnt lgkmcnt(6)
	v_mfma_f32_32x32x16_bf16 v[32:47], v[192:195], v[200:203], v[32:47]
	v_max3_f32 v145, v145, v93, v94
	v_max3_f32 v237, v237, v77, v78
	v_max_f32_e32 v145, v145, v95
	s_waitcnt lgkmcnt(5)
	v_mfma_f32_32x32x16_bf16 v[32:47], v[228:231], v[212:215], v[32:47]
	v_max_f32_e32 v237, v237, v79
	v_max_f32_e32 v145, v145, v237
	ds_bpermute_b32 v237, v158, v145
	s_waitcnt lgkmcnt(5)
	v_mfma_f32_32x32x16_bf16 v[32:47], v[232:235], v[216:219], v[32:47]
	v_add_u32_e32 v239, v131, v164
	s_waitcnt vmcnt(3)
	ds_write_b128 v239, v[116:119] offset:17408
	ds_read_b128 v[188:191], v147 offset:48640
	ds_read_b128 v[192:195], v147 offset:48672
	ds_read_b128 v[228:231], v147 offset:48704
	ds_read_b128 v[232:235], v147 offset:48736
	s_waitcnt lgkmcnt(9)
	v_mfma_f32_32x32x16_bf16 v[16:31], v[172:175], v[196:199], v[16:31]
	v_add_u32_e32 v239, v131, v165
	s_waitcnt vmcnt(2)
	ds_write_b128 v239, v[112:115] offset:17408
	s_waitcnt lgkmcnt(9)
	v_mfma_f32_32x32x16_bf16 v[16:31], v[176:179], v[200:203], v[16:31]
	v_add_u32_e32 v239, v156, v166
	s_waitcnt vmcnt(1)
	ds_write_b128 v239, v[124:127] offset:34816
	s_waitcnt lgkmcnt(9)
	v_mfma_f32_32x32x16_bf16 v[16:31], v[180:183], v[212:215], v[16:31]
	v_add_u32_e32 v239, v156, v167
	s_waitcnt vmcnt(0)
	ds_write_b128 v239, v[120:123] offset:34816
	s_waitcnt lgkmcnt(9)
	v_mfma_f32_32x32x16_bf16 v[16:31], v[184:187], v[216:219], v[16:31]
	s_waitcnt lgkmcnt(8)
	v_max_f32_e32 v237, v145, v237
	v_add_f32_e32 v239, 0x41000000, v149
	v_max_f32_e32 v145, v149, v237
	s_waitcnt lgkmcnt(6)
	v_mfma_f32_32x32x16_bf16 v[0:15], v[188:191], v[196:199], v[0:15]
	v_sub_f32_e32 v238, v149, v145
	v_cmp_gt_f32_e32 vcc, v237, v239
	v_exp_f32_e32 v238, v238
	s_waitcnt lgkmcnt(5)
	v_mfma_f32_32x32x16_bf16 v[0:15], v[192:195], v[200:203], v[0:15]
	s_waitcnt lgkmcnt(4)
	v_mfma_f32_32x32x16_bf16 v[0:15], v[228:231], v[212:215], v[0:15]
	s_waitcnt lgkmcnt(3)
	v_mfma_f32_32x32x16_bf16 v[0:15], v[232:235], v[216:219], v[0:15]
	s_cbranch_vccz .Lat_keepm_4
	v_mov_b32_e32 v149, v145
.Lat_keepm_4:
	s_add_i32 s21, s21, 64
	s_add_i32 s20, s20, 1
	s_waitcnt lgkmcnt(0)
	s_barrier
	s_branch .Lat_loop
